# P5/P12: next tile's row sums + shift vector loaded during the current epilogue (moved to v243-251 at its end) instead of at the tile header
# baseline (speedup 1.0000x reference)
;     DEV void operator()(const f32x4 (&acc)[2][2][4][2], const Unit& u, int wr, int wc, int fr, int fq) const {
;     ...
;         if (FUSED) { const int b = u.pm >> 4; const float* sp = shw + (size_t)b * NFF2 + u.pn * 256 + wc * 32 + 8 * fq;
;             sg[0] = *(const f32x4*)sp; sg[1] = *(const f32x4*)(sp + 4); su[0] = *(const f32x4*)(sp + 128); su[1] = *(const f32x4*)(sp + 132); }
;     DEV void operator()(const f32x4 (&acc)[2][2][4][2], const Unit& u, int wr, int wc, int fr, int fq) const {
;     ...
;         float rstd8[8]; row_rstd8(rs, row0, fq, rstd8);
.LBB0_478:
	s_cmp_lg_u32 s93, 0
	s_cbranch_scc1 .Lp5_hskip
	s_lshl_b32 s100, s6, 8
	s_add_u32 s100, s100, s73
	v_add_u32_e32 v252, s100, v147
	v_lshlrev_b32_e32 v252, 2, v252
	s_add_u32 s98, s88, 0x3c900000
	s_addc_u32 s99, s89, 0
	global_load_dword v243, v252, s[98:99] offset:0
	global_load_dword v244, v252, s[98:99] offset:64
	global_load_dword v245, v252, s[98:99] offset:128
	global_load_dword v246, v252, s[98:99] offset:192
	global_load_dword v247, v252, s[98:99] offset:512
	global_load_dword v248, v252, s[98:99] offset:576
	global_load_dword v249, v252, s[98:99] offset:640
	global_load_dword v250, v252, s[98:99] offset:704
	s_ashr_i32 s100, s6, 4
	s_min_i32 s100, s100, 16
	s_mul_i32 s100, s100, 0x2c00
	s_lshl_b32 s101, s10, 10
	s_add_u32 s100, s100, s101
	s_lshl_b32 s101, s74, 2
	s_add_u32 s100, s100, s101
	s_add_u32 s98, s88, 0x3d200000
	s_addc_u32 s99, s89, 0
	s_add_u32 s98, s98, s100
	s_addc_u32 s99, s99, 0
	v_and_b32_e32 v253, 31, v204
	v_lshrrev_b32_e32 v254, 5, v204
	v_lshl_add_u32 v253, v254, 7, v253
	v_lshlrev_b32_e32 v253, 2, v253
	global_load_dword v251, v253, s[98:99]

;     DEV void operator()(const f32x4 (&acc)[2][2][4][2], const Unit& u, int wr, int wc, int fr, int fq) const {
;     ...
;         if (FUSED) { const int b = u.pm >> 4; const float* sp = shw + (size_t)b * NFF2 + u.pn * 256 + wc * 32 + 8 * fq;
;             sg[0] = *(const f32x4*)sp; sg[1] = *(const f32x4*)(sp + 4); su[0] = *(const f32x4*)(sp + 128); su[1] = *(const f32x4*)(sp + 132); }
;     DEV void operator()(const f32x4 (&acc)[2][2][4][2], const Unit& u, int wr, int wc, int fr, int fq) const {
;     ...
;         float rstd8[8]; row_rstd8(rs, row0, fq, rstd8);
.LBB0_484:
	s_waitcnt vmcnt(8)
	s_cmp_lg_u64 s[4:5], 0
	s_cbranch_scc0 .Lp5_nonext
	s_lshl_b32 s100, s40, 8
	s_add_u32 s100, s100, s73
	v_add_u32_e32 v252, s100, v147
	v_lshlrev_b32_e32 v252, 2, v252
	s_add_u32 s98, s88, 0x3c900000
	s_addc_u32 s99, s89, 0
	global_load_dword v206, v252, s[98:99] offset:0
	global_load_dword v207, v252, s[98:99] offset:64
	global_load_dword v208, v252, s[98:99] offset:128
	global_load_dword v209, v252, s[98:99] offset:192
	global_load_dword v210, v252, s[98:99] offset:512
	global_load_dword v211, v252, s[98:99] offset:576
	global_load_dword v212, v252, s[98:99] offset:640
	global_load_dword v213, v252, s[98:99] offset:704
	s_ashr_i32 s100, s40, 4
	s_min_i32 s100, s100, 16
	s_mul_i32 s100, s100, 0x2c00
	s_lshl_b32 s101, s38, 10
	s_add_u32 s100, s100, s101
	s_lshl_b32 s101, s74, 2
	s_add_u32 s100, s100, s101
	s_add_u32 s98, s88, 0x3d200000
	s_addc_u32 s99, s89, 0
	s_add_u32 s98, s98, s100
	s_addc_u32 s99, s99, 0
	v_and_b32_e32 v253, 31, v204
	v_lshrrev_b32_e32 v254, 5, v204
	v_lshl_add_u32 v253, v254, 7, v253
	v_lshlrev_b32_e32 v253, 2, v253
	global_load_dword v214, v253, s[98:99]
.Lp5_nonext:
	v_mov_b32_e32 v174, 0x358637bd
	s_mov_b32 s7, 0x3a800000
	v_fma_f32 v243, v243, s7, v174
	v_fma_f32 v244, v244, s7, v174
	v_fma_f32 v245, v245, s7, v174
	v_fma_f32 v246, v246, s7, v174
	v_fma_f32 v247, v247, s7, v174
	v_fma_f32 v248, v248, s7, v174
	v_fma_f32 v249, v249, s7, v174
	v_fma_f32 v250, v250, s7, v174
	v_rsq_f32_e32 v243, v243
	v_rsq_f32_e32 v244, v244
	v_rsq_f32_e32 v245, v245
	v_rsq_f32_e32 v246, v246
	v_rsq_f32_e32 v247, v247
	v_rsq_f32_e32 v248, v248
	v_rsq_f32_e32 v249, v249
	v_rsq_f32_e32 v250, v250
	s_lshl_b32 s11, s73, 4
	s_lshl_b32 s7, s74, 3
	s_add_u32 s11, s11, s7
	s_add_u32 s11, s11, 0x20000
	v_lshl_add_u32 v175, v204, 2, s11
	ds_write_b32 v175, v251
	v_lshl_add_u32 v176, v165, 5, s11
	s_lshl_b32 s12, s6, 8
	s_add_u32 s12, s12, s73
	s_lshl_b32 s7, s10, 8
	s_or_b32 s7, s7, s74
	v_add_u32_e32 v177, s12, v147
	v_mul_u32_u24_e32 v178, 0x1600, v177
	v_lshl_add_u32 v179, v165, 3, s7
	v_lshl_add_u32 v178, v179, 1, v178
	s_add_u32 s48, s88, 0xc800000
	s_addc_u32 s49, s89, 0
	s_mov_b32 s33, 0x3d372713
	v_mov_b32_e32 v183, 0
	v_mov_b32_e32 v184, 0
	v_mov_b32_e32 v185, 0
	v_mov_b32_e32 v186, 0
	v_mov_b32_e32 v187, 0
	v_mov_b32_e32 v188, 0
	v_mov_b32_e32 v189, 0
	v_mov_b32_e32 v190, 0
	s_waitcnt lgkmcnt(0)
	ds_read_b128 v[22:25], v176
	ds_read_b128 v[30:33], v176 offset:16
	ds_read_b128 v[38:41], v176 offset:128
	ds_read_b128 v[46:49], v176 offset:144
	s_waitcnt lgkmcnt(0)
	s_cmp_lt_i32 s10, 4
	s_cbranch_scc1 .Lp5_act0
	s_cmp_gt_i32 s10, 9
	s_cbranch_scc1 .Lp5_act0
	s_cmp_lt_i32 s10, 6
	s_cbranch_scc1 .Lp5_act1

;     DEV void operator()(const f32x4 (&acc)[2][2][4][2], const Unit& u, int wr, int wc, int fr, int fq) const {
;     ...
;         if (FUSED) { const int b = u.pm >> 4; const float* sp = shw + (size_t)b * NFF2 + u.pn * 256 + wc * 32 + 8 * fq;
;             sg[0] = *(const f32x4*)sp; sg[1] = *(const f32x4*)(sp + 4); su[0] = *(const f32x4*)(sp + 128); su[1] = *(const f32x4*)(sp + 132); }
;     DEV void operator()(const f32x4 (&acc)[2][2][4][2], const Unit& u, int wr, int wc, int fr, int fq) const {
;     ...
;         float rstd8[8]; row_rstd8(rs, row0, fq, rstd8);
.Lp5_done:
	s_cmp_lg_u64 s[4:5], 0
	s_cbranch_scc0 .Lp5_nomov
	s_waitcnt vmcnt(16)
	v_mov_b32_e32 v243, v206
	v_mov_b32_e32 v244, v207
	v_mov_b32_e32 v245, v208
	v_mov_b32_e32 v246, v209
	v_mov_b32_e32 v247, v210
	v_mov_b32_e32 v248, v211
	v_mov_b32_e32 v249, v212
	v_mov_b32_e32 v250, v213
	v_mov_b32_e32 v251, v214

;     DEV void operator()(const f32x4 (&acc)[2][2][4][2], const Unit& u, int wr, int wc, int fr, int fq) const {
;     ...
;         if (FUSED) { const int b = u.pm >> 4; const float* sp = shw + (size_t)b * NFF2 + u.pn * 256 + wc * 32 + 8 * fq;
;             sg[0] = *(const f32x4*)sp; sg[1] = *(const f32x4*)(sp + 4); su[0] = *(const f32x4*)(sp + 128); su[1] = *(const f32x4*)(sp + 132); }
;     ...
;         if (FUSED) row_rstd8(rs, row0, fq, rstd8);
.LBB0_1892:
	s_cmp_lg_u32 s41, 0
	s_cbranch_scc1 .Lp12_hskip
	s_lshl_b32 s100, s0, 8
	s_add_u32 s100, s100, s44
	v_add_u32_e32 v252, s100, v147
	v_lshlrev_b32_e32 v252, 2, v252
	s_add_u32 s98, s88, 0x3ce00000
	s_addc_u32 s99, s89, 0
	global_load_dword v243, v252, s[98:99] offset:0
	global_load_dword v244, v252, s[98:99] offset:64
	global_load_dword v245, v252, s[98:99] offset:128
	global_load_dword v246, v252, s[98:99] offset:192
	global_load_dword v247, v252, s[98:99] offset:512
	global_load_dword v248, v252, s[98:99] offset:576
	global_load_dword v249, v252, s[98:99] offset:640
	global_load_dword v250, v252, s[98:99] offset:704
	s_ashr_i32 s100, s0, 4
	s_mul_i32 s100, s100, 0x5800
	s_lshl_b32 s101, s1, 10
	s_add_u32 s100, s100, s101
	s_lshl_b32 s101, s45, 2
	s_add_u32 s100, s100, s101
	s_add_u32 s98, s88, 0x3d300000
	s_addc_u32 s99, s89, 0
	s_add_u32 s98, s98, s100
	s_addc_u32 s99, s99, 0
	v_and_b32_e32 v253, 31, v191
	v_lshrrev_b32_e32 v254, 5, v191
	v_lshl_add_u32 v253, v254, 7, v253
	v_lshlrev_b32_e32 v253, 2, v253
	global_load_dword v251, v253, s[98:99]

; DEV float silu_f(float x) { return x * __builtin_amdgcn_rcpf(1.f + __expf(-x)); }
; DEV u32x4 pack8(const float (&f)[8]) { u32x4 w; w.x = cvt_pk_bf16(f[0], f[1]); w.y = cvt_pk_bf16(f[2], f[3]); w.z = cvt_pk_bf16(f[4], f[5]); w.w = cvt_pk_bf16(f[6], f[7]); return w; }
;     DEV void operator()(const f32x4 (&acc)[2][2][4][2], const Unit& u, int wr, int wc, int fr, int fq) const {
;         asm volatile("" : "+v"(fr), "+v"(fq));
;         const int row0 = u.pm * 256 + wr * 64 + fr, col0 = u.pn * 128 + wc * 32 + 8 * fq;
;         f32x4 sg[2], su[2];
;         if (FUSED) { const int b = u.pm >> 4; const float* sp = shw + (size_t)b * NFF2 + u.pn * 256 + wc * 32 + 8 * fq;
;             sg[0] = *(const f32x4*)sp; sg[1] = *(const f32x4*)(sp + 4); su[0] = *(const f32x4*)(sp + 128); su[1] = *(const f32x4*)(sp + 132); }
;         float rstd8[8];
;         if (FUSED) row_rstd8(rs, row0, fq, rstd8);
; #pragma unroll
;         for (int ai = 0; ai < 2; ++ai)
; #pragma unroll
;             for (int m = 0; m < 4; ++m) {
;                 const int row = row0 + ai * 128 + m * 16;
;                 const float rstd = FUSED ? rstd8[ai * 4 + m] : 1.f;
;                 float h[8];
; #pragma unroll
;                 for (int n = 0; n < 2; ++n)
; #pragma unroll
;                     for (int j = 0; j < 4; ++j) { float g = acc[ai][0][m][n][j], up = acc[ai][1][m][n][j]; if (FUSED) { g = g * rstd + sg[n][j]; up = up * rstd + su[n][j]; } h[4 * n + j] = silu_f(g) * up; }
;                 *(u32x4*)(H + (size_t)row * DFF + col0) = pack8(h);
;             }
.LBB0_1898:
	s_waitcnt vmcnt(8)
	s_cmp_lg_u64 s[4:5], 0
	s_cbranch_scc0 .Lp12_nonext
	s_lshl_b32 s100, s24, 8
	s_add_u32 s100, s100, s44
	v_add_u32_e32 v252, s100, v147
	v_lshlrev_b32_e32 v252, 2, v252
	s_add_u32 s98, s88, 0x3ce00000
	s_addc_u32 s99, s89, 0
	global_load_dword v206, v252, s[98:99] offset:0
	global_load_dword v207, v252, s[98:99] offset:64
	global_load_dword v208, v252, s[98:99] offset:128
	global_load_dword v209, v252, s[98:99] offset:192
	global_load_dword v210, v252, s[98:99] offset:512
	global_load_dword v211, v252, s[98:99] offset:576
	global_load_dword v212, v252, s[98:99] offset:640
	global_load_dword v213, v252, s[98:99] offset:704
	s_ashr_i32 s100, s24, 4
	s_mul_i32 s100, s100, 0x5800
	s_lshl_b32 s101, s22, 10
	s_add_u32 s100, s100, s101
	s_lshl_b32 s101, s45, 2
	s_add_u32 s100, s100, s101
	s_add_u32 s98, s88, 0x3d300000
	s_addc_u32 s99, s89, 0
	s_add_u32 s98, s98, s100
	s_addc_u32 s99, s99, 0
	v_and_b32_e32 v253, 31, v191
	v_lshrrev_b32_e32 v254, 5, v191
	v_lshl_add_u32 v253, v254, 7, v253
	v_lshlrev_b32_e32 v253, 2, v253
	global_load_dword v214, v253, s[98:99]
.Lp12_nonext:
	v_mov_b32_e32 v200, 0x358637bd
	s_mov_b32 s6, 0x3a800000
	v_fma_f32 v243, v243, s6, v200
	v_fma_f32 v244, v244, s6, v200
	v_fma_f32 v245, v245, s6, v200
	v_fma_f32 v246, v246, s6, v200
	v_fma_f32 v247, v247, s6, v200
	v_fma_f32 v248, v248, s6, v200
	v_fma_f32 v249, v249, s6, v200
	v_fma_f32 v250, v250, s6, v200
	v_rsq_f32_e32 v243, v243
	v_rsq_f32_e32 v244, v244
	v_rsq_f32_e32 v245, v245
	v_rsq_f32_e32 v246, v246
	v_rsq_f32_e32 v247, v247
	v_rsq_f32_e32 v248, v248
	v_rsq_f32_e32 v249, v249
	v_rsq_f32_e32 v250, v250
	s_lshl_b32 s7, s44, 4
	s_lshl_b32 s6, s45, 3
	s_add_u32 s7, s7, s6
	s_add_u32 s7, s7, 0x20000
	v_lshl_add_u32 v201, v191, 2, s7
	ds_write_b32 v201, v251
	v_lshl_add_u32 v202, v171, 5, s7
	s_lshl_b32 s23, s0, 8
	s_add_u32 s23, s23, s44
	s_lshl_b32 s6, s1, 7
	s_or_b32 s6, s6, s45
	v_add_u32_e32 v203, s23, v147
	v_mul_u32_u24_e32 v204, 0x1600, v203
	v_lshl_add_u32 v205, v171, 3, s6
	v_lshl_add_u32 v204, v205, 1, v204
	s_waitcnt lgkmcnt(0)
	ds_read_b128 v[130:133], v202
	ds_read_b128 v[134:137], v202 offset:16
	ds_read_b128 v[138:141], v202 offset:128
	ds_read_b128 v[142:145], v202 offset:144
	s_waitcnt lgkmcnt(0)
	v_fma_f32 v126, v126, v243, v130
	v_fma_f32 v127, v127, v243, v131
	v_fma_f32 v128, v128, v243, v132
	v_fma_f32 v129, v129, v243, v133
	v_fma_f32 v122, v122, v243, v134
	v_fma_f32 v123, v123, v243, v135
	v_fma_f32 v124, v124, v243, v136
	v_fma_f32 v125, v125, v243, v137
	v_mul_f32_e32 v192, 0xbfb8aa3b, v126
	v_mul_f32_e32 v193, 0xbfb8aa3b, v127
	v_mul_f32_e32 v194, 0xbfb8aa3b, v128
	v_mul_f32_e32 v195, 0xbfb8aa3b, v129
	v_mul_f32_e32 v196, 0xbfb8aa3b, v122
	v_mul_f32_e32 v197, 0xbfb8aa3b, v123
	v_mul_f32_e32 v198, 0xbfb8aa3b, v124
	v_mul_f32_e32 v199, 0xbfb8aa3b, v125
	v_exp_f32_e32 v192, v192
	v_exp_f32_e32 v193, v193
	v_exp_f32_e32 v194, v194
	v_exp_f32_e32 v195, v195
	v_exp_f32_e32 v196, v196
	v_exp_f32_e32 v197, v197
	v_exp_f32_e32 v198, v198
	v_exp_f32_e32 v199, v199
	v_fma_f32 v118, v118, v243, v138
	v_fma_f32 v119, v119, v243, v139
	v_fma_f32 v120, v120, v243, v140
	v_fma_f32 v121, v121, v243, v141
	v_fma_f32 v114, v114, v243, v142
	v_fma_f32 v115, v115, v243, v143
	v_fma_f32 v116, v116, v243, v144
	v_fma_f32 v117, v117, v243, v145
	v_add_f32_e32 v192, 1.0, v192
	v_add_f32_e32 v193, 1.0, v193
	v_add_f32_e32 v194, 1.0, v194
	v_add_f32_e32 v195, 1.0, v195
	v_add_f32_e32 v196, 1.0, v196
	v_add_f32_e32 v197, 1.0, v197
	v_add_f32_e32 v198, 1.0, v198
	v_add_f32_e32 v199, 1.0, v199
	v_rcp_f32_e32 v192, v192
	v_rcp_f32_e32 v193, v193
	v_rcp_f32_e32 v194, v194
	v_rcp_f32_e32 v195, v195
	v_rcp_f32_e32 v196, v196
	v_rcp_f32_e32 v197, v197
	v_rcp_f32_e32 v198, v198
	v_rcp_f32_e32 v199, v199
	v_mul_f32_e32 v126, v126, v118
	v_mul_f32_e32 v127, v127, v119
	v_mul_f32_e32 v128, v128, v120
	v_mul_f32_e32 v129, v129, v121
	v_mul_f32_e32 v122, v122, v114
	v_mul_f32_e32 v123, v123, v115
	v_mul_f32_e32 v124, v124, v116
	v_mul_f32_e32 v125, v125, v117
	v_mul_f32_e32 v126, v126, v192
	v_mul_f32_e32 v127, v127, v193
	v_mul_f32_e32 v128, v128, v194
	v_mul_f32_e32 v129, v129, v195
	v_mul_f32_e32 v122, v122, v196
	v_mul_f32_e32 v123, v123, v197
	v_mul_f32_e32 v124, v124, v198
	v_mul_f32_e32 v125, v125, v199
	v_cvt_pk_bf16_f32 v118, v126, v127
	v_cvt_pk_bf16_f32 v119, v128, v129
	v_cvt_pk_bf16_f32 v120, v122, v123
	v_cvt_pk_bf16_f32 v121, v124, v125
	global_store_dwordx4 v204, v[118:121], s[56:57]
	v_fma_f32 v110, v110, v244, v130
	v_fma_f32 v111, v111, v244, v131
	v_fma_f32 v112, v112, v244, v132
	v_fma_f32 v113, v113, v244, v133
	v_fma_f32 v106, v106, v244, v134
	v_fma_f32 v107, v107, v244, v135
	v_fma_f32 v108, v108, v244, v136
	v_fma_f32 v109, v109, v244, v137
	v_mul_f32_e32 v192, 0xbfb8aa3b, v110
	v_mul_f32_e32 v193, 0xbfb8aa3b, v111
	v_mul_f32_e32 v194, 0xbfb8aa3b, v112
	v_mul_f32_e32 v195, 0xbfb8aa3b, v113
	v_mul_f32_e32 v196, 0xbfb8aa3b, v106
	v_mul_f32_e32 v197, 0xbfb8aa3b, v107
	v_mul_f32_e32 v198, 0xbfb8aa3b, v108
	v_mul_f32_e32 v199, 0xbfb8aa3b, v109
	v_exp_f32_e32 v192, v192
	v_exp_f32_e32 v193, v193
	v_exp_f32_e32 v194, v194
	v_exp_f32_e32 v195, v195
	v_exp_f32_e32 v196, v196
	v_exp_f32_e32 v197, v197
	v_exp_f32_e32 v198, v198
	v_exp_f32_e32 v199, v199
	v_fma_f32 v102, v102, v244, v138
	v_fma_f32 v103, v103, v244, v139
	v_fma_f32 v104, v104, v244, v140
	v_fma_f32 v105, v105, v244, v141
	v_fma_f32 v98, v98, v244, v142
	v_fma_f32 v99, v99, v244, v143
	v_fma_f32 v100, v100, v244, v144
	v_fma_f32 v101, v101, v244, v145
	v_add_f32_e32 v192, 1.0, v192
	v_add_f32_e32 v193, 1.0, v193
	v_add_f32_e32 v194, 1.0, v194
	v_add_f32_e32 v195, 1.0, v195
; DEV float silu_f(float x) { return x * __builtin_amdgcn_rcpf(1.f + __expf(-x)); }
; DEV u32x4 pack8(const float (&f)[8]) { u32x4 w; w.x = cvt_pk_bf16(f[0], f[1]); w.y = cvt_pk_bf16(f[2], f[3]); w.z = cvt_pk_bf16(f[4], f[5]); w.w = cvt_pk_bf16(f[6], f[7]); return w; }
;     DEV void operator()(const f32x4 (&acc)[2][2][4][2], const Unit& u, int wr, int wc, int fr, int fq) const {
;     ...
; #pragma unroll
;                 for (int n = 0; n < 2; ++n)
; #pragma unroll
;                     for (int j = 0; j < 4; ++j) { float g = acc[ai][0][m][n][j], up = acc[ai][1][m][n][j]; if (FUSED) { g = g * rstd + sg[n][j]; up = up * rstd + su[n][j]; } h[4 * n + j] = silu_f(g) * up; }
;                 *(u32x4*)(H + (size_t)row * DFF + col0) = pack8(h);
	v_add_f32_e32 v196, 1.0, v196
	v_add_f32_e32 v197, 1.0, v197
	v_add_f32_e32 v198, 1.0, v198
	v_add_f32_e32 v199, 1.0, v199
	v_rcp_f32_e32 v192, v192
	v_rcp_f32_e32 v193, v193
	v_rcp_f32_e32 v194, v194
	v_rcp_f32_e32 v195, v195
	v_rcp_f32_e32 v196, v196
	v_rcp_f32_e32 v197, v197
	v_rcp_f32_e32 v198, v198
	v_rcp_f32_e32 v199, v199
	v_mul_f32_e32 v110, v110, v102
	v_mul_f32_e32 v111, v111, v103
	v_mul_f32_e32 v112, v112, v104
	v_mul_f32_e32 v113, v113, v105
	v_mul_f32_e32 v106, v106, v98
	v_mul_f32_e32 v107, v107, v99
	v_mul_f32_e32 v108, v108, v100
	v_mul_f32_e32 v109, v109, v101
	v_mul_f32_e32 v110, v110, v192
	v_mul_f32_e32 v111, v111, v193
	v_mul_f32_e32 v112, v112, v194
	v_mul_f32_e32 v113, v113, v195
	v_mul_f32_e32 v106, v106, v196
	v_mul_f32_e32 v107, v107, v197
	v_mul_f32_e32 v108, v108, v198
	v_mul_f32_e32 v109, v109, v199
	v_cvt_pk_bf16_f32 v102, v110, v111
	v_cvt_pk_bf16_f32 v103, v112, v113
	v_cvt_pk_bf16_f32 v104, v106, v107
	v_cvt_pk_bf16_f32 v105, v108, v109
	s_add_u32 s98, s56, 0x16000
	s_addc_u32 s99, s57, 0
	global_store_dwordx4 v204, v[102:105], s[98:99]
	v_fma_f32 v94, v94, v245, v130
	v_fma_f32 v95, v95, v245, v131
	v_fma_f32 v96, v96, v245, v132
	v_fma_f32 v97, v97, v245, v133
	v_fma_f32 v90, v90, v245, v134
	v_fma_f32 v91, v91, v245, v135
	v_fma_f32 v92, v92, v245, v136
	v_fma_f32 v93, v93, v245, v137
	v_mul_f32_e32 v192, 0xbfb8aa3b, v94
	v_mul_f32_e32 v193, 0xbfb8aa3b, v95
	v_mul_f32_e32 v194, 0xbfb8aa3b, v96
	v_mul_f32_e32 v195, 0xbfb8aa3b, v97
	v_mul_f32_e32 v196, 0xbfb8aa3b, v90
	v_mul_f32_e32 v197, 0xbfb8aa3b, v91
	v_mul_f32_e32 v198, 0xbfb8aa3b, v92
	v_mul_f32_e32 v199, 0xbfb8aa3b, v93
	v_exp_f32_e32 v192, v192
	v_exp_f32_e32 v193, v193
	v_exp_f32_e32 v194, v194
	v_exp_f32_e32 v195, v195
	v_exp_f32_e32 v196, v196
	v_exp_f32_e32 v197, v197
	v_exp_f32_e32 v198, v198
	v_exp_f32_e32 v199, v199
	v_fma_f32 v86, v86, v245, v138
	v_fma_f32 v87, v87, v245, v139
	v_fma_f32 v88, v88, v245, v140
	v_fma_f32 v89, v89, v245, v141
	v_fma_f32 v82, v82, v245, v142
	v_fma_f32 v83, v83, v245, v143
	v_fma_f32 v84, v84, v245, v144
	v_fma_f32 v85, v85, v245, v145
	v_add_f32_e32 v192, 1.0, v192
	v_add_f32_e32 v193, 1.0, v193
	v_add_f32_e32 v194, 1.0, v194
	v_add_f32_e32 v195, 1.0, v195
	v_add_f32_e32 v196, 1.0, v196
	v_add_f32_e32 v197, 1.0, v197
	v_add_f32_e32 v198, 1.0, v198
	v_add_f32_e32 v199, 1.0, v199
	v_rcp_f32_e32 v192, v192
	v_rcp_f32_e32 v193, v193
	v_rcp_f32_e32 v194, v194
	v_rcp_f32_e32 v195, v195
	v_rcp_f32_e32 v196, v196
	v_rcp_f32_e32 v197, v197
	v_rcp_f32_e32 v198, v198
	v_rcp_f32_e32 v199, v199
	v_mul_f32_e32 v94, v94, v86
	v_mul_f32_e32 v95, v95, v87
	v_mul_f32_e32 v96, v96, v88
	v_mul_f32_e32 v97, v97, v89
	v_mul_f32_e32 v90, v90, v82
	v_mul_f32_e32 v91, v91, v83
	v_mul_f32_e32 v92, v92, v84
	v_mul_f32_e32 v93, v93, v85
	v_mul_f32_e32 v94, v94, v192
	v_mul_f32_e32 v95, v95, v193
	v_mul_f32_e32 v96, v96, v194
	v_mul_f32_e32 v97, v97, v195
	v_mul_f32_e32 v90, v90, v196
	v_mul_f32_e32 v91, v91, v197
	v_mul_f32_e32 v92, v92, v198
	v_mul_f32_e32 v93, v93, v199
	v_cvt_pk_bf16_f32 v86, v94, v95
	v_cvt_pk_bf16_f32 v87, v96, v97
	v_cvt_pk_bf16_f32 v88, v90, v91
	v_cvt_pk_bf16_f32 v89, v92, v93
	s_add_u32 s98, s56, 0x2c000
	s_addc_u32 s99, s57, 0
	global_store_dwordx4 v204, v[86:89], s[98:99]
	v_fma_f32 v78, v78, v246, v130
	v_fma_f32 v79, v79, v246, v131
	v_fma_f32 v80, v80, v246, v132
	v_fma_f32 v81, v81, v246, v133
	v_fma_f32 v74, v74, v246, v134
	v_fma_f32 v75, v75, v246, v135
	v_fma_f32 v76, v76, v246, v136
	v_fma_f32 v77, v77, v246, v137
	v_mul_f32_e32 v192, 0xbfb8aa3b, v78
	v_mul_f32_e32 v193, 0xbfb8aa3b, v79
	v_mul_f32_e32 v194, 0xbfb8aa3b, v80
	v_mul_f32_e32 v195, 0xbfb8aa3b, v81
	v_mul_f32_e32 v196, 0xbfb8aa3b, v74
	v_mul_f32_e32 v197, 0xbfb8aa3b, v75
	v_mul_f32_e32 v198, 0xbfb8aa3b, v76
	v_mul_f32_e32 v199, 0xbfb8aa3b, v77
	v_exp_f32_e32 v192, v192
	v_exp_f32_e32 v193, v193
	v_exp_f32_e32 v194, v194
	v_exp_f32_e32 v195, v195
	v_exp_f32_e32 v196, v196
	v_exp_f32_e32 v197, v197
	v_exp_f32_e32 v198, v198
	v_exp_f32_e32 v199, v199
	v_fma_f32 v70, v70, v246, v138
	v_fma_f32 v71, v71, v246, v139
	v_fma_f32 v72, v72, v246, v140
	v_fma_f32 v73, v73, v246, v141
	v_fma_f32 v66, v66, v246, v142
	v_fma_f32 v67, v67, v246, v143
	v_fma_f32 v68, v68, v246, v144
	v_fma_f32 v69, v69, v246, v145
	v_add_f32_e32 v192, 1.0, v192
	v_add_f32_e32 v193, 1.0, v193
	v_add_f32_e32 v194, 1.0, v194
	v_add_f32_e32 v195, 1.0, v195
	v_add_f32_e32 v196, 1.0, v196
	v_add_f32_e32 v197, 1.0, v197
	v_add_f32_e32 v198, 1.0, v198
	v_add_f32_e32 v199, 1.0, v199
	v_rcp_f32_e32 v192, v192
	v_rcp_f32_e32 v193, v193
	v_rcp_f32_e32 v194, v194
	v_rcp_f32_e32 v195, v195
	v_rcp_f32_e32 v196, v196
	v_rcp_f32_e32 v197, v197
	v_rcp_f32_e32 v198, v198
	v_rcp_f32_e32 v199, v199
	v_mul_f32_e32 v78, v78, v70
	v_mul_f32_e32 v79, v79, v71
	v_mul_f32_e32 v80, v80, v72
	v_mul_f32_e32 v81, v81, v73
	v_mul_f32_e32 v74, v74, v66
	v_mul_f32_e32 v75, v75, v67
	v_mul_f32_e32 v76, v76, v68
	v_mul_f32_e32 v77, v77, v69
	v_mul_f32_e32 v78, v78, v192
	v_mul_f32_e32 v79, v79, v193
	v_mul_f32_e32 v80, v80, v194
	v_mul_f32_e32 v81, v81, v195
	v_mul_f32_e32 v74, v74, v196
	v_mul_f32_e32 v75, v75, v197
	v_mul_f32_e32 v76, v76, v198
	v_mul_f32_e32 v77, v77, v199
	v_cvt_pk_bf16_f32 v70, v78, v79
	v_cvt_pk_bf16_f32 v71, v80, v81
	v_cvt_pk_bf16_f32 v72, v74, v75
	v_cvt_pk_bf16_f32 v73, v76, v77
	s_add_u32 s98, s56, 0x42000
	s_addc_u32 s99, s57, 0
	global_store_dwordx4 v204, v[70:73], s[98:99]
	v_fma_f32 v62, v62, v247, v130
	v_fma_f32 v63, v63, v247, v131
	v_fma_f32 v64, v64, v247, v132
	v_fma_f32 v65, v65, v247, v133
	v_fma_f32 v58, v58, v247, v134
	v_fma_f32 v59, v59, v247, v135
; DEV float silu_f(float x) { return x * __builtin_amdgcn_rcpf(1.f + __expf(-x)); }
; DEV u32x4 pack8(const float (&f)[8]) { u32x4 w; w.x = cvt_pk_bf16(f[0], f[1]); w.y = cvt_pk_bf16(f[2], f[3]); w.z = cvt_pk_bf16(f[4], f[5]); w.w = cvt_pk_bf16(f[6], f[7]); return w; }
;     DEV void operator()(const f32x4 (&acc)[2][2][4][2], const Unit& u, int wr, int wc, int fr, int fq) const {
;     ...
;                 const float rstd = FUSED ? rstd8[ai * 4 + m] : 1.f;
;                 float h[8];
; #pragma unroll
;                 for (int n = 0; n < 2; ++n)
; #pragma unroll
;                     for (int j = 0; j < 4; ++j) { float g = acc[ai][0][m][n][j], up = acc[ai][1][m][n][j]; if (FUSED) { g = g * rstd + sg[n][j]; up = up * rstd + su[n][j]; } h[4 * n + j] = silu_f(g) * up; }
;                 *(u32x4*)(H + (size_t)row * DFF + col0) = pack8(h);
	v_fma_f32 v60, v60, v247, v136
	v_fma_f32 v61, v61, v247, v137
	v_mul_f32_e32 v192, 0xbfb8aa3b, v62
	v_mul_f32_e32 v193, 0xbfb8aa3b, v63
	v_mul_f32_e32 v194, 0xbfb8aa3b, v64
	v_mul_f32_e32 v195, 0xbfb8aa3b, v65
	v_mul_f32_e32 v196, 0xbfb8aa3b, v58
	v_mul_f32_e32 v197, 0xbfb8aa3b, v59
	v_mul_f32_e32 v198, 0xbfb8aa3b, v60
	v_mul_f32_e32 v199, 0xbfb8aa3b, v61
	v_exp_f32_e32 v192, v192
	v_exp_f32_e32 v193, v193
	v_exp_f32_e32 v194, v194
	v_exp_f32_e32 v195, v195
	v_exp_f32_e32 v196, v196
	v_exp_f32_e32 v197, v197
	v_exp_f32_e32 v198, v198
	v_exp_f32_e32 v199, v199
	v_fma_f32 v54, v54, v247, v138
	v_fma_f32 v55, v55, v247, v139
	v_fma_f32 v56, v56, v247, v140
	v_fma_f32 v57, v57, v247, v141
	v_fma_f32 v50, v50, v247, v142
	v_fma_f32 v51, v51, v247, v143
	v_fma_f32 v52, v52, v247, v144
	v_fma_f32 v53, v53, v247, v145
	v_add_f32_e32 v192, 1.0, v192
	v_add_f32_e32 v193, 1.0, v193
	v_add_f32_e32 v194, 1.0, v194
	v_add_f32_e32 v195, 1.0, v195
	v_add_f32_e32 v196, 1.0, v196
	v_add_f32_e32 v197, 1.0, v197
	v_add_f32_e32 v198, 1.0, v198
	v_add_f32_e32 v199, 1.0, v199
	v_rcp_f32_e32 v192, v192
	v_rcp_f32_e32 v193, v193
	v_rcp_f32_e32 v194, v194
	v_rcp_f32_e32 v195, v195
	v_rcp_f32_e32 v196, v196
	v_rcp_f32_e32 v197, v197
	v_rcp_f32_e32 v198, v198
	v_rcp_f32_e32 v199, v199
	v_mul_f32_e32 v62, v62, v54
	v_mul_f32_e32 v63, v63, v55
	v_mul_f32_e32 v64, v64, v56
	v_mul_f32_e32 v65, v65, v57
	v_mul_f32_e32 v58, v58, v50
	v_mul_f32_e32 v59, v59, v51
	v_mul_f32_e32 v60, v60, v52
	v_mul_f32_e32 v61, v61, v53
	v_mul_f32_e32 v62, v62, v192
	v_mul_f32_e32 v63, v63, v193
	v_mul_f32_e32 v64, v64, v194
	v_mul_f32_e32 v65, v65, v195
	v_mul_f32_e32 v58, v58, v196
	v_mul_f32_e32 v59, v59, v197
	v_mul_f32_e32 v60, v60, v198
	v_mul_f32_e32 v61, v61, v199
	v_cvt_pk_bf16_f32 v54, v62, v63
	v_cvt_pk_bf16_f32 v55, v64, v65
	v_cvt_pk_bf16_f32 v56, v58, v59
	v_cvt_pk_bf16_f32 v57, v60, v61
	s_add_u32 s98, s56, 0xb0000
	s_addc_u32 s99, s57, 0
	global_store_dwordx4 v204, v[54:57], s[98:99]
	v_fma_f32 v46, v46, v248, v130
	v_fma_f32 v47, v47, v248, v131
	v_fma_f32 v48, v48, v248, v132
	v_fma_f32 v49, v49, v248, v133
	v_fma_f32 v42, v42, v248, v134
	v_fma_f32 v43, v43, v248, v135
	v_fma_f32 v44, v44, v248, v136
	v_fma_f32 v45, v45, v248, v137
	v_mul_f32_e32 v192, 0xbfb8aa3b, v46
	v_mul_f32_e32 v193, 0xbfb8aa3b, v47
	v_mul_f32_e32 v194, 0xbfb8aa3b, v48
	v_mul_f32_e32 v195, 0xbfb8aa3b, v49
	v_mul_f32_e32 v196, 0xbfb8aa3b, v42
	v_mul_f32_e32 v197, 0xbfb8aa3b, v43
	v_mul_f32_e32 v198, 0xbfb8aa3b, v44
	v_mul_f32_e32 v199, 0xbfb8aa3b, v45
	v_exp_f32_e32 v192, v192
	v_exp_f32_e32 v193, v193
	v_exp_f32_e32 v194, v194
	v_exp_f32_e32 v195, v195
	v_exp_f32_e32 v196, v196
	v_exp_f32_e32 v197, v197
	v_exp_f32_e32 v198, v198
	v_exp_f32_e32 v199, v199
	v_fma_f32 v38, v38, v248, v138
	v_fma_f32 v39, v39, v248, v139
	v_fma_f32 v40, v40, v248, v140
	v_fma_f32 v41, v41, v248, v141
	v_fma_f32 v34, v34, v248, v142
	v_fma_f32 v35, v35, v248, v143
	v_fma_f32 v36, v36, v248, v144
	v_fma_f32 v37, v37, v248, v145
	v_add_f32_e32 v192, 1.0, v192
	v_add_f32_e32 v193, 1.0, v193
	v_add_f32_e32 v194, 1.0, v194
	v_add_f32_e32 v195, 1.0, v195
	v_add_f32_e32 v196, 1.0, v196
	v_add_f32_e32 v197, 1.0, v197
	v_add_f32_e32 v198, 1.0, v198
	v_add_f32_e32 v199, 1.0, v199
	v_rcp_f32_e32 v192, v192
	v_rcp_f32_e32 v193, v193
	v_rcp_f32_e32 v194, v194
	v_rcp_f32_e32 v195, v195
	v_rcp_f32_e32 v196, v196
	v_rcp_f32_e32 v197, v197
	v_rcp_f32_e32 v198, v198
	v_rcp_f32_e32 v199, v199
	v_mul_f32_e32 v46, v46, v38
	v_mul_f32_e32 v47, v47, v39
	v_mul_f32_e32 v48, v48, v40
	v_mul_f32_e32 v49, v49, v41
	v_mul_f32_e32 v42, v42, v34
	v_mul_f32_e32 v43, v43, v35
	v_mul_f32_e32 v44, v44, v36
	v_mul_f32_e32 v45, v45, v37
	v_mul_f32_e32 v46, v46, v192
	v_mul_f32_e32 v47, v47, v193
	v_mul_f32_e32 v48, v48, v194
	v_mul_f32_e32 v49, v49, v195
	v_mul_f32_e32 v42, v42, v196
	v_mul_f32_e32 v43, v43, v197
	v_mul_f32_e32 v44, v44, v198
	v_mul_f32_e32 v45, v45, v199
	v_cvt_pk_bf16_f32 v38, v46, v47
	v_cvt_pk_bf16_f32 v39, v48, v49
	v_cvt_pk_bf16_f32 v40, v42, v43
	v_cvt_pk_bf16_f32 v41, v44, v45
	s_add_u32 s98, s56, 0xc6000
	s_addc_u32 s99, s57, 0
	global_store_dwordx4 v204, v[38:41], s[98:99]
	v_fma_f32 v30, v30, v249, v130
	v_fma_f32 v31, v31, v249, v131
	v_fma_f32 v32, v32, v249, v132
	v_fma_f32 v33, v33, v249, v133
	v_fma_f32 v26, v26, v249, v134
	v_fma_f32 v27, v27, v249, v135
	v_fma_f32 v28, v28, v249, v136
	v_fma_f32 v29, v29, v249, v137
	v_mul_f32_e32 v192, 0xbfb8aa3b, v30
	v_mul_f32_e32 v193, 0xbfb8aa3b, v31
; #define PG8_BAR __builtin_amdgcn_s_barrier()
; DEV float silu_f(float x) { return x * __builtin_amdgcn_rcpf(1.f + __expf(-x)); }
; DEV u32x4 pack8(const float (&f)[8]) { u32x4 w; w.x = cvt_pk_bf16(f[0], f[1]); w.y = cvt_pk_bf16(f[2], f[3]); w.z = cvt_pk_bf16(f[4], f[5]); w.w = cvt_pk_bf16(f[6], f[7]); return w; }
; template <class Epi, class Sched, bool ALIGN_EPI = false, bool SP2 = false>
; __device__ __forceinline__ void gemm_phase(PG8_LAS unsigned char* lds, const Gemm g, const Sched& S, const Epi& E) {
;     ...
;         if (!has_next) break;
; #pragma unroll
;         for (int a = 0; a < 2; ++a)
; #pragma unroll
;             for (int b = 0; b < 2; ++b)
; #pragma unroll
;                 for (int m = 0; m < 4; ++m)
; #pragma unroll
;                     for (int n = 0; n < 2; ++n) acc[a][b][m][n] = (f32x4){0.f, 0.f, 0.f, 0.f};
;         cur = nxt; cA = nA; cB = nB; ++ui;
;         if constexpr (ALIGN_EPI) { if (wr == 1) PG8_BAR; }
;     DEV void operator()(const f32x4 (&acc)[2][2][4][2], const Unit& u, int wr, int wc, int fr, int fq) const {
;     ...
;                 const float rstd = FUSED ? rstd8[ai * 4 + m] : 1.f;
;                 float h[8];
; #pragma unroll
;                 for (int n = 0; n < 2; ++n)
; #pragma unroll
;                     for (int j = 0; j < 4; ++j) { float g = acc[ai][0][m][n][j], up = acc[ai][1][m][n][j]; if (FUSED) { g = g * rstd + sg[n][j]; up = up * rstd + su[n][j]; } h[4 * n + j] = silu_f(g) * up; }
;                 *(u32x4*)(H + (size_t)row * DFF + col0) = pack8(h);
	v_mul_f32_e32 v194, 0xbfb8aa3b, v32
	v_mul_f32_e32 v195, 0xbfb8aa3b, v33
	v_mul_f32_e32 v196, 0xbfb8aa3b, v26
	v_mul_f32_e32 v197, 0xbfb8aa3b, v27
	v_mul_f32_e32 v198, 0xbfb8aa3b, v28
	v_mul_f32_e32 v199, 0xbfb8aa3b, v29
	v_exp_f32_e32 v192, v192
	v_exp_f32_e32 v193, v193
	v_exp_f32_e32 v194, v194
	v_exp_f32_e32 v195, v195
	v_exp_f32_e32 v196, v196
	v_exp_f32_e32 v197, v197
	v_exp_f32_e32 v198, v198
	v_exp_f32_e32 v199, v199
	v_fma_f32 v22, v22, v249, v138
	v_fma_f32 v23, v23, v249, v139
	v_fma_f32 v24, v24, v249, v140
	v_fma_f32 v25, v25, v249, v141
	v_fma_f32 v18, v18, v249, v142
	v_fma_f32 v19, v19, v249, v143
	v_fma_f32 v20, v20, v249, v144
	v_fma_f32 v21, v21, v249, v145
	v_add_f32_e32 v192, 1.0, v192
	v_add_f32_e32 v193, 1.0, v193
	v_add_f32_e32 v194, 1.0, v194
	v_add_f32_e32 v195, 1.0, v195
	v_add_f32_e32 v196, 1.0, v196
	v_add_f32_e32 v197, 1.0, v197
	v_add_f32_e32 v198, 1.0, v198
	v_add_f32_e32 v199, 1.0, v199
	v_rcp_f32_e32 v192, v192
	v_rcp_f32_e32 v193, v193
	v_rcp_f32_e32 v194, v194
	v_rcp_f32_e32 v195, v195
	v_rcp_f32_e32 v196, v196
	v_rcp_f32_e32 v197, v197
	v_rcp_f32_e32 v198, v198
	v_rcp_f32_e32 v199, v199
	v_mul_f32_e32 v30, v30, v22
	v_mul_f32_e32 v31, v31, v23
	v_mul_f32_e32 v32, v32, v24
	v_mul_f32_e32 v33, v33, v25
	v_mul_f32_e32 v26, v26, v18
	v_mul_f32_e32 v27, v27, v19
	v_mul_f32_e32 v28, v28, v20
	v_mul_f32_e32 v29, v29, v21
	v_mul_f32_e32 v30, v30, v192
	v_mul_f32_e32 v31, v31, v193
	v_mul_f32_e32 v32, v32, v194
	v_mul_f32_e32 v33, v33, v195
	v_mul_f32_e32 v26, v26, v196
	v_mul_f32_e32 v27, v27, v197
	v_mul_f32_e32 v28, v28, v198
	v_mul_f32_e32 v29, v29, v199
	v_cvt_pk_bf16_f32 v22, v30, v31
	v_cvt_pk_bf16_f32 v23, v32, v33
	v_cvt_pk_bf16_f32 v24, v26, v27
	v_cvt_pk_bf16_f32 v25, v28, v29
	s_add_u32 s98, s56, 0xdc000
	s_addc_u32 s99, s57, 0
	global_store_dwordx4 v204, v[22:25], s[98:99]
	v_fma_f32 v14, v14, v250, v130
	v_fma_f32 v15, v15, v250, v131
	v_fma_f32 v16, v16, v250, v132
	v_fma_f32 v17, v17, v250, v133
	v_fma_f32 v10, v10, v250, v134
	v_fma_f32 v11, v11, v250, v135
	v_fma_f32 v12, v12, v250, v136
	v_fma_f32 v13, v13, v250, v137
	v_mul_f32_e32 v192, 0xbfb8aa3b, v14
	v_mul_f32_e32 v193, 0xbfb8aa3b, v15
	v_mul_f32_e32 v194, 0xbfb8aa3b, v16
	v_mul_f32_e32 v195, 0xbfb8aa3b, v17
	v_mul_f32_e32 v196, 0xbfb8aa3b, v10
	v_mul_f32_e32 v197, 0xbfb8aa3b, v11
	v_mul_f32_e32 v198, 0xbfb8aa3b, v12
	v_mul_f32_e32 v199, 0xbfb8aa3b, v13
	v_exp_f32_e32 v192, v192
	v_exp_f32_e32 v193, v193
	v_exp_f32_e32 v194, v194
	v_exp_f32_e32 v195, v195
	v_exp_f32_e32 v196, v196
	v_exp_f32_e32 v197, v197
	v_exp_f32_e32 v198, v198
	v_exp_f32_e32 v199, v199
	v_fma_f32 v6, v6, v250, v138
	v_fma_f32 v7, v7, v250, v139
	v_fma_f32 v8, v8, v250, v140
	v_fma_f32 v9, v9, v250, v141
	v_fma_f32 v2, v2, v250, v142
	v_fma_f32 v3, v3, v250, v143
	v_fma_f32 v4, v4, v250, v144
	v_fma_f32 v5, v5, v250, v145
	v_add_f32_e32 v192, 1.0, v192
	v_add_f32_e32 v193, 1.0, v193
	v_add_f32_e32 v194, 1.0, v194
	v_add_f32_e32 v195, 1.0, v195
	v_add_f32_e32 v196, 1.0, v196
	v_add_f32_e32 v197, 1.0, v197
	v_add_f32_e32 v198, 1.0, v198
	v_add_f32_e32 v199, 1.0, v199
	v_rcp_f32_e32 v192, v192
	v_rcp_f32_e32 v193, v193
	v_rcp_f32_e32 v194, v194
	v_rcp_f32_e32 v195, v195
	v_rcp_f32_e32 v196, v196
	v_rcp_f32_e32 v197, v197
	v_rcp_f32_e32 v198, v198
	v_rcp_f32_e32 v199, v199
	v_mul_f32_e32 v14, v14, v6
	v_mul_f32_e32 v15, v15, v7
	v_mul_f32_e32 v16, v16, v8
	v_mul_f32_e32 v17, v17, v9
	v_mul_f32_e32 v10, v10, v2
	v_mul_f32_e32 v11, v11, v3
	v_mul_f32_e32 v12, v12, v4
	v_mul_f32_e32 v13, v13, v5
	v_mul_f32_e32 v14, v14, v192
	v_mul_f32_e32 v15, v15, v193
	v_mul_f32_e32 v16, v16, v194
	v_mul_f32_e32 v17, v17, v195
	v_mul_f32_e32 v10, v10, v196
	v_mul_f32_e32 v11, v11, v197
	v_mul_f32_e32 v12, v12, v198
	v_mul_f32_e32 v13, v13, v199
	v_cvt_pk_bf16_f32 v6, v14, v15
	v_cvt_pk_bf16_f32 v7, v16, v17
	v_cvt_pk_bf16_f32 v8, v10, v11
	v_cvt_pk_bf16_f32 v9, v12, v13
	s_add_u32 s98, s56, 0xf2000
	s_addc_u32 s99, s57, 0
	global_store_dwordx4 v204, v[6:9], s[98:99]
	s_cmp_lg_u64 s[4:5], 0
	s_cbranch_scc0 .Lp12_nomov
	s_waitcnt vmcnt(8)
	v_mov_b32_e32 v243, v206
	v_mov_b32_e32 v244, v207
	v_mov_b32_e32 v245, v208
	v_mov_b32_e32 v246, v209
	v_mov_b32_e32 v247, v210
	v_mov_b32_e32 v248, v211
	v_mov_b32_e32 v249, v212
	v_mov_b32_e32 v250, v213
	v_mov_b32_e32 v251, v214
.Lp12_nomov:
	s_andn2_b64 vcc, exec, s[4:5]
	s_mov_b64 s[0:1], -1
	s_cbranch_vccnz .LBB0_1891
	s_andn2_b64 vcc, exec, s[10:11]
	s_cbranch_vccnz .LBB0_1890
	s_barrier
	s_branch .LBB0_1890
